# code placement: 4-byte unreachable pad ahead of the GEMM section (all GEMM loop heads shift by 4 bytes)
# baseline (speedup 1.0000x reference)
; #define LAS __attribute__((address_space(3)))
; template <int MODE>
; __device__ __forceinline__ void small_gemm(const bf16_t* A, const bf16_t* Bt, int Npos, int K, const LAS unsigned long long* eap, LAS unsigned char* lds, int wg, int G, int wid, int lane) {
;     const int fr = lane & 15, fq = lane >> 4, ncg = (MODE == 0 ? (ABIN + 63) / 64 : Npos / 64), nunits = (TS / 16) * ncg, KW = K / 8;
;     LAS f32x4* part = (LAS f32x4*)lds;
;     for (int u = wg; u < nunits; u += G) {
;         const int rb = u % (TS / 16), cgp = u / (TS / 16), r0 = TP + rb * 16, p0 = cgp * 64;
;         f32x4 acc[4];
; #pragma unroll
;         for (int f = 0; f < 4; ++f) acc[f] = (f32x4){0.f, 0.f, 0.f, 0.f};
;         const bf16_t* ap = A + (size_t)(r0 + fr) * K + wid * KW + 8 * fq;
;         const bf16_t* bp = Bt + (size_t)(p0 + fr) * K + wid * KW + 8 * fq;
; __global__ void __launch_bounds__(512, 2) hybrid_fwd(Params P) {
;     ...
;                 g.N = Npos;
;                 __syncthreads();
;                 pg8::StaticOrder S; S.init(TP, Npos, G, wg);
;                 if (mode == 0) { small_gemm<0>(g.A, g.Bt, Npos, g.K, eap, lds, wg, G, wid, lane); Epi<0> E{eap}; pg8::gemm_phase<Epi<0>, true, true>(lds, g, S, E, tid); }
;                 else if (mode == 1) { small_gemm<1>(g.A, g.Bt, Npos, g.K, eap, lds, wg, G, wid, lane); Epi<1> E{eap}; pg8::gemm_phase<Epi<1>, true, true>(lds, g, S, E, tid); }
;                 else if (mode == 2) { small_gemm<2>(g.A, g.Bt, Npos, g.K, eap, lds, wg, G, wid, lane); Epi<2> E{eap}; pg8::gemm_phase<Epi<2>, true, true>(lds, g, S, E, tid); }
;                 else { small_gemm<3>(g.A, g.Bt, Npos, g.K, eap, lds, wg, G, wid, lane); Epi<3> E{eap}; pg8::gemm_phase<Epi<3>, true, true>(lds, g, S, E, tid); }
.LBB0_287:
	s_andn2_b64 vcc, exec, s[56:57]
	s_cbranch_vccnz .LBB0_552
	s_mov_b64 s[0:1], -1
	s_lshr_b32 s11, s69, 5
	s_lshr_b32 s16, s69, 1
	s_andn2_b64 vcc, exec, s[18:19]
	v_and_b32_e32 v165, 15, v166
	s_waitcnt lgkmcnt(0)
	s_barrier
	s_cbranch_vccz .LBB0_438
	s_xor_b64 s[12:13], s[28:29], -1
	s_lshr_b32 s49, s69, 3
	s_lshr_b32 s96, s48, 3
	s_cmp_lt_i32 s94, s49
	s_cselect_b64 s[0:1], -1, 0
	s_cmp_ge_i32 s94, s49
	v_or_b32_e32 v167, 0x8000, v165
	s_cselect_b64 s[56:57], -1, 0
	s_mov_b64 s[18:19], -1
	s_and_b64 vcc, exec, s[12:13]
	s_cbranch_vccz .LBB0_369
	s_xor_b64 s[12:13], s[82:83], -1
	s_and_b64 vcc, exec, s[12:13]
	s_cbranch_vccz .LBB0_319
	s_andn2_b64 vcc, exec, s[0:1]
	s_cbranch_vccnz .LBB0_298
	s_mul_i32 s12, s96, s61
	s_waitcnt vmcnt(16)
	v_mul_u32_u24_e64 v1, s48, 48
	s_ashr_i32 s13, s12, 31
	s_lshl_b32 s2, s61, 12
	v_lshrrev_b32_e32 v0, 2, v164
	s_waitcnt vmcnt(12)
	v_lshlrev_b32_e32 v2, 1, v1
	v_mov_b32_e32 v3, v161
	s_cmp_lt_u32 s76, 64
	v_and_b32_e32 v0, 12, v0
	v_and_b32_e32 v160, 48, v166
	v_lshl_add_u64 v[2:3], s[62:63], 0, v[2:3]
	v_lshl_add_u32 v42, v164, 4, 0
	s_cselect_b64 s[0:1], -1, 0
	s_lshl_b64 s[18:19], s[12:13], 1
	s_waitcnt vmcnt(3)
	v_lshl_add_u64 v[18:19], s[70:71], 0, v[160:161]
	s_lshl_b32 s4, s48, 1
	s_waitcnt vmcnt(0)
	v_lshl_add_u64 v[20:21], s[62:63], 0, v[160:161]
	v_lshl_add_u64 v[22:23], v[2:3], 0, v[160:161]
	v_lshlrev_b32_e32 v24, 1, v0
	s_mov_b32 s12, s94
	s_branch .LBB0_294
	s_nop 0
